# code-placement check: v47 with one extra 4-byte s_nop at kernel entry (shifts every loop by 4 bytes)
# speedup vs baseline: 1.0127x; 1.0018x over previous
; #define LAS __attribute__((address_space(3)))
; __device__ __forceinline__ unsigned xb_add(unsigned* p, unsigned v) { return __hip_atomic_fetch_add(p, v, __ATOMIC_RELAXED, __HIP_MEMORY_SCOPE_AGENT); }
; __device__ __forceinline__ unsigned xb_xcc_id() { return (unsigned)__builtin_amdgcn_s_getreg((3 << 11) | 20) & 0xFu; }
; __device__ __forceinline__ XcdBarrier xcd_barrier_post(unsigned* bar, volatile LAS unsigned* st) {
;     XcdBarrier b; b.bar = bar; b.x = xb_xcc_id(); b.st = st;
;     if (threadIdx.x == 0) (void)xb_add(&bar[XB_XCNT(b.x)], 1u);
;     return b;
; __global__ void __launch_bounds__(NTHR) mk_fwd(Args args) {
;     __shared__ __attribute__((aligned(16))) unsigned char lds_raw[LDS_BYTES];
;     LAS unsigned char* lds = (LAS unsigned char*)lds_raw;
;     cg::grid_group grid = cg::this_grid();
;     const int tid = threadIdx.x, lane = tid & 63, wave = __builtin_amdgcn_readfirstlane(tid >> 6);
;     const int G = gridDim.x, gw = blockIdx.x * NWAVES + wave, NGW = G * NWAVES;
;     CArgs* ap = (CArgs*)__builtin_amdgcn_kernarg_segment_ptr();
;     ...
;     const int lo = ap->ph_lo, hi = ap->ph_hi;
;     ...
;     constexpr int lo = 0, hi = N_PHASES;
;     ...
;     int ph = 0;
;     ...
;     if (tid < 32) MISCP[tid] = 0u;
;     __syncthreads();
;     if (hi - lo > 1) (void)xcd_barrier_post((unsigned*)(ap->ws + ap->ws_off + WS_CTL), MISCP + 8);
_Z6mk_fwd4Args:
	s_load_dwordx2 s[14:15], s[0:1], 0xe0
	s_nop 0
	s_load_dword s46, s[0:1], 0xe8
	s_mov_b64 s[92:93], s[0:1]
	s_add_u32 s4, s92, 0xe0
	v_and_b32_e32 v145, 0x3ff, v0
	s_mov_b32 s96, s2
	s_addc_u32 s5, s93, 0
	v_readfirstlane_b32 s47, v145
	v_cmp_gt_u32_e32 vcc, 32, v145
	s_and_saveexec_b64 s[0:1], vcc
	v_mov_b32_e32 v1, 0x20140
	v_lshl_add_u32 v1, v145, 2, v1
	v_mov_b32_e32 v2, 0
	ds_write_b32 v1, v2
	v_writelane_b32 v252, s4, 0
	s_nop 1
	v_writelane_b32 v252, s5, 1
	s_or_b64 exec, exec, s[0:1]
	s_waitcnt lgkmcnt(0)
	s_barrier
	s_getreg_b32 s4, hwreg(HW_REG_XCC_ID, 0, 4)
	v_cmp_eq_u32_e64 s[2:3], 0, v145
	s_mov_b64 s[0:1], exec
	s_nop 0
	v_writelane_b32 v252, s2, 2
	s_nop 1
	v_writelane_b32 v252, s3, 3
	s_and_b64 s[2:3], s[0:1], s[2:3]
	s_mov_b64 exec, s[2:3]
	s_cbranch_execz .LBB0_5
	s_mov_b64 s[2:3], exec
	v_mbcnt_lo_u32_b32 v1, s2, 0
	v_mbcnt_hi_u32_b32 v1, s3, v1
	v_cmp_eq_u32_e32 vcc, 0, v1
	s_and_b64 s[6:7], exec, vcc
	s_mov_b64 exec, s[6:7]
	s_cbranch_execz .LBB0_5
	s_load_dwordx4 s[8:11], s[92:93], 0xc8
	v_mov_b32_e32 v1, 0x11500000
	s_waitcnt lgkmcnt(0)
	s_add_u32 s5, s8, s10
	s_addc_u32 s6, s9, s11
	s_lshl_b32 s4, s4, 8
	s_and_b32 s4, s4, 0xf00
	s_add_u32 s4, s5, s4
	s_addc_u32 s5, s6, 0
	s_bcnt1_i32_b64 s2, s[2:3]
	v_mov_b32_e32 v2, s2
	global_atomic_add v1, v2, s[4:5] offset:1024
